# hand-written grid barrier: XCD-last block bumps 16 per-XCD TOP replicas (no return), each XCD's leaders poll their own replica
# speedup vs baseline: 1.0090x; 1.0070x over previous
.LBB0_146:
	s_or_b64 exec, exec, s[4:5]
	s_cmp_lt_u32 s61, 2
	s_cbranch_scc1 .LBB0_200
	s_waitcnt vmcnt(0) lgkmcnt(0)
	s_barrier
	v_readfirstlane_b32 s2, v162
	s_lshl_b32 s3, s33, 8
	s_add_u32 s6, s84, s3
	s_addc_u32 s7, s85, 0
	s_cmp_lg_u32 s2, 0
	s_cbranch_scc1 .Lgb1_wait
	s_mov_b64 s[8:9], exec
	s_mov_b64 exec, 1
	v_mov_b32_e32 v0, 0x12000
	ds_read_b64 v[2:3], v0
	v_mov_b32_e32 v0, 0x1400
	v_mov_b32_e32 v1, 1
	global_atomic_add v4, v0, v1, s[6:7] sc0
	s_mov_b32 s13, 0
	s_add_u32 s14, s84, 0x2480
	s_addc_u32 s15, s85, 0
	s_waitcnt lgkmcnt(0)
	v_readfirstlane_b32 s10, v2
	v_readfirstlane_b32 s11, v3
	v_mov_b32_e32 v0, 0
	s_nop 3
	s_mul_i32 s10, s10, 2
	s_mul_i32 s11, s11, 1
	s_waitcnt vmcnt(0)
	v_readfirstlane_b32 s12, v4
	s_nop 3
	s_add_u32 s12, s12, 1
	s_cmp_lg_u32 s12, s10
	s_cbranch_scc1 .Lgb1_poll
	buffer_wbl2 sc1
	s_waitcnt vmcnt(0)
	global_atomic_add v0, v1, s[14:15] offset:0
	global_atomic_add v0, v1, s[14:15] offset:256
	global_atomic_add v0, v1, s[14:15] offset:512
	global_atomic_add v0, v1, s[14:15] offset:768
	global_atomic_add v0, v1, s[14:15] offset:1024
	global_atomic_add v0, v1, s[14:15] offset:1280
	global_atomic_add v0, v1, s[14:15] offset:1536
	global_atomic_add v0, v1, s[14:15] offset:1792
	global_atomic_add v0, v1, s[14:15] offset:2048
	global_atomic_add v0, v1, s[14:15] offset:2304
	global_atomic_add v0, v1, s[14:15] offset:2560
	global_atomic_add v0, v1, s[14:15] offset:2816
	global_atomic_add v0, v1, s[14:15] offset:3072
	global_atomic_add v0, v1, s[14:15] offset:3328
	global_atomic_add v0, v1, s[14:15] offset:3584
	global_atomic_add v0, v1, s[14:15] offset:3840
.Lgb1_poll:
	v_mov_b32_e32 v0, 0x2480
.Lgb1_loop:
	global_load_dword v4, v0, s[6:7] sc1
	s_add_u32 s13, s13, 1
	s_waitcnt vmcnt(0)
	v_readfirstlane_b32 s12, v4
	s_nop 3
	s_cmp_gt_u32 s13, 0x80000
	s_cbranch_scc1 .Lgb1_done
	s_cmp_ge_u32 s12, s11
	s_cbranch_scc1 .Lgb1_done
	s_sleep 1
	s_branch .Lgb1_loop

.LBB0_418:
	s_cmp_lt_i32 s61, 3
	s_cbranch_scc1 .LBB0_472
	s_waitcnt vmcnt(0) lgkmcnt(0)
	s_barrier
	v_readfirstlane_b32 s2, v162
	s_lshl_b32 s3, s33, 8
	s_add_u32 s6, s84, s3
	s_addc_u32 s7, s85, 0
	s_cmp_lg_u32 s2, 0
	s_cbranch_scc1 .Lgb2_wait
	s_mov_b64 s[8:9], exec
	s_mov_b64 exec, 1
	v_mov_b32_e32 v0, 0x12000
	ds_read_b64 v[2:3], v0
	v_mov_b32_e32 v0, 0x1400
	v_mov_b32_e32 v1, 1
	global_atomic_add v4, v0, v1, s[6:7] sc0
	s_mov_b32 s13, 0
	s_add_u32 s14, s84, 0x2480
	s_addc_u32 s15, s85, 0
	s_waitcnt lgkmcnt(0)
	v_readfirstlane_b32 s10, v2
	v_readfirstlane_b32 s11, v3
	v_mov_b32_e32 v0, 0
	s_nop 3
	s_mul_i32 s10, s10, 3
	s_mul_i32 s11, s11, 2
	s_waitcnt vmcnt(0)
	v_readfirstlane_b32 s12, v4
	s_nop 3
	s_add_u32 s12, s12, 1
	s_cmp_lg_u32 s12, s10
	s_cbranch_scc1 .Lgb2_poll
	buffer_wbl2 sc1
	s_waitcnt vmcnt(0)
	global_atomic_add v0, v1, s[14:15] offset:0
	global_atomic_add v0, v1, s[14:15] offset:256
	global_atomic_add v0, v1, s[14:15] offset:512
	global_atomic_add v0, v1, s[14:15] offset:768
	global_atomic_add v0, v1, s[14:15] offset:1024
	global_atomic_add v0, v1, s[14:15] offset:1280
	global_atomic_add v0, v1, s[14:15] offset:1536
	global_atomic_add v0, v1, s[14:15] offset:1792
	global_atomic_add v0, v1, s[14:15] offset:2048
	global_atomic_add v0, v1, s[14:15] offset:2304
	global_atomic_add v0, v1, s[14:15] offset:2560
	global_atomic_add v0, v1, s[14:15] offset:2816
	global_atomic_add v0, v1, s[14:15] offset:3072
	global_atomic_add v0, v1, s[14:15] offset:3328
	global_atomic_add v0, v1, s[14:15] offset:3584
	global_atomic_add v0, v1, s[14:15] offset:3840

.LBB0_491:
	s_or_b64 exec, exec, s[4:5]
	s_cmp_lt_i32 s61, 4
	s_cbranch_scc1 .LBB0_545
	s_waitcnt vmcnt(0) lgkmcnt(0)
	s_barrier
	v_readfirstlane_b32 s2, v162
	s_lshl_b32 s3, s33, 8
	s_add_u32 s6, s84, s3
	s_addc_u32 s7, s85, 0
	s_cmp_lg_u32 s2, 0
	s_cbranch_scc1 .Lgb3_wait
	s_mov_b64 s[8:9], exec
	s_mov_b64 exec, 1
	v_mov_b32_e32 v0, 0x12000
	ds_read_b64 v[2:3], v0
	v_mov_b32_e32 v0, 0x1400
	v_mov_b32_e32 v1, 1
	global_atomic_add v4, v0, v1, s[6:7] sc0
	s_mov_b32 s13, 0
	s_add_u32 s14, s84, 0x2480
	s_addc_u32 s15, s85, 0
	s_waitcnt lgkmcnt(0)
	v_readfirstlane_b32 s10, v2
	v_readfirstlane_b32 s11, v3
	v_mov_b32_e32 v0, 0
	s_nop 3
	s_mul_i32 s10, s10, 4
	s_mul_i32 s11, s11, 3
	s_waitcnt vmcnt(0)
	v_readfirstlane_b32 s12, v4
	s_nop 3
	s_add_u32 s12, s12, 1
	s_cmp_lg_u32 s12, s10
	s_cbranch_scc1 .Lgb3_poll
	buffer_wbl2 sc1
	s_waitcnt vmcnt(0)
	global_atomic_add v0, v1, s[14:15] offset:0
	global_atomic_add v0, v1, s[14:15] offset:256
	global_atomic_add v0, v1, s[14:15] offset:512
	global_atomic_add v0, v1, s[14:15] offset:768
	global_atomic_add v0, v1, s[14:15] offset:1024
	global_atomic_add v0, v1, s[14:15] offset:1280
	global_atomic_add v0, v1, s[14:15] offset:1536
	global_atomic_add v0, v1, s[14:15] offset:1792
	global_atomic_add v0, v1, s[14:15] offset:2048
	global_atomic_add v0, v1, s[14:15] offset:2304
	global_atomic_add v0, v1, s[14:15] offset:2560
	global_atomic_add v0, v1, s[14:15] offset:2816
	global_atomic_add v0, v1, s[14:15] offset:3072
	global_atomic_add v0, v1, s[14:15] offset:3328
	global_atomic_add v0, v1, s[14:15] offset:3584
	global_atomic_add v0, v1, s[14:15] offset:3840

.LBB0_721:
	s_cmp_lt_i32 s61, 5
	s_cbranch_scc1 .LBB0_775
	s_waitcnt vmcnt(0) lgkmcnt(0)
	s_barrier
	v_readfirstlane_b32 s2, v162
	s_lshl_b32 s3, s33, 8
	s_add_u32 s6, s84, s3
	s_addc_u32 s7, s85, 0
	s_cmp_lg_u32 s2, 0
	s_cbranch_scc1 .Lgb4_wait
	s_mov_b64 s[8:9], exec
	s_mov_b64 exec, 1
	v_mov_b32_e32 v0, 0x12000
	ds_read_b64 v[2:3], v0
	v_mov_b32_e32 v0, 0x1400
	v_mov_b32_e32 v1, 1
	global_atomic_add v4, v0, v1, s[6:7] sc0
	s_mov_b32 s13, 0
	s_add_u32 s14, s84, 0x2480
	s_addc_u32 s15, s85, 0
	s_waitcnt lgkmcnt(0)
	v_readfirstlane_b32 s10, v2
	v_readfirstlane_b32 s11, v3
	v_mov_b32_e32 v0, 0
	s_nop 3
	s_mul_i32 s10, s10, 5
	s_mul_i32 s11, s11, 4
	s_waitcnt vmcnt(0)
	v_readfirstlane_b32 s12, v4
	s_nop 3
	s_add_u32 s12, s12, 1
	s_cmp_lg_u32 s12, s10
	s_cbranch_scc1 .Lgb4_poll
	buffer_wbl2 sc1
	s_waitcnt vmcnt(0)
	global_atomic_add v0, v1, s[14:15] offset:0
	global_atomic_add v0, v1, s[14:15] offset:256
	global_atomic_add v0, v1, s[14:15] offset:512
	global_atomic_add v0, v1, s[14:15] offset:768
	global_atomic_add v0, v1, s[14:15] offset:1024
	global_atomic_add v0, v1, s[14:15] offset:1280
	global_atomic_add v0, v1, s[14:15] offset:1536
	global_atomic_add v0, v1, s[14:15] offset:1792
	global_atomic_add v0, v1, s[14:15] offset:2048
	global_atomic_add v0, v1, s[14:15] offset:2304
	global_atomic_add v0, v1, s[14:15] offset:2560
	global_atomic_add v0, v1, s[14:15] offset:2816
	global_atomic_add v0, v1, s[14:15] offset:3072
	global_atomic_add v0, v1, s[14:15] offset:3328
	global_atomic_add v0, v1, s[14:15] offset:3584
	global_atomic_add v0, v1, s[14:15] offset:3840

.LBB0_779:
	s_or_b64 exec, exec, s[8:9]
	s_cmp_lt_u32 s61, 6
	s_cbranch_scc1 .LBB0_833
	s_waitcnt vmcnt(0) lgkmcnt(0)
	s_barrier
	v_readfirstlane_b32 s2, v162
	s_lshl_b32 s3, s33, 8
	s_add_u32 s6, s84, s3
	s_addc_u32 s7, s85, 0
	s_cmp_lg_u32 s2, 0
	s_cbranch_scc1 .Lgb5_wait
	s_mov_b64 s[8:9], exec
	s_mov_b64 exec, 1
	v_mov_b32_e32 v0, 0x12000
	ds_read_b64 v[2:3], v0
	v_mov_b32_e32 v0, 0x1400
	v_mov_b32_e32 v1, 1
	global_atomic_add v4, v0, v1, s[6:7] sc0
	s_mov_b32 s13, 0
	s_add_u32 s14, s84, 0x2480
	s_addc_u32 s15, s85, 0
	s_waitcnt lgkmcnt(0)
	v_readfirstlane_b32 s10, v2
	v_readfirstlane_b32 s11, v3
	v_mov_b32_e32 v0, 0
	s_nop 3
	s_mul_i32 s10, s10, 6
	s_mul_i32 s11, s11, 5
	s_waitcnt vmcnt(0)
	v_readfirstlane_b32 s12, v4
	s_nop 3
	s_add_u32 s12, s12, 1
	s_cmp_lg_u32 s12, s10
	s_cbranch_scc1 .Lgb5_poll
	buffer_wbl2 sc1
	s_waitcnt vmcnt(0)
	global_atomic_add v0, v1, s[14:15] offset:0
	global_atomic_add v0, v1, s[14:15] offset:256
	global_atomic_add v0, v1, s[14:15] offset:512
	global_atomic_add v0, v1, s[14:15] offset:768
	global_atomic_add v0, v1, s[14:15] offset:1024
	global_atomic_add v0, v1, s[14:15] offset:1280
	global_atomic_add v0, v1, s[14:15] offset:1536
	global_atomic_add v0, v1, s[14:15] offset:1792
	global_atomic_add v0, v1, s[14:15] offset:2048
	global_atomic_add v0, v1, s[14:15] offset:2304
	global_atomic_add v0, v1, s[14:15] offset:2560
	global_atomic_add v0, v1, s[14:15] offset:2816
	global_atomic_add v0, v1, s[14:15] offset:3072
	global_atomic_add v0, v1, s[14:15] offset:3328
	global_atomic_add v0, v1, s[14:15] offset:3584
	global_atomic_add v0, v1, s[14:15] offset:3840

.LBB0_897:
	s_or_b64 exec, exec, s[10:11]
	s_cmp_lt_u32 s61, 8
	s_cbranch_scc1 .LBB0_951
	s_waitcnt vmcnt(0) lgkmcnt(0)
	s_barrier
	v_readfirstlane_b32 s2, v162
	s_lshl_b32 s3, s33, 8
	s_add_u32 s6, s84, s3
	s_addc_u32 s7, s85, 0
	s_cmp_lg_u32 s2, 0
	s_cbranch_scc1 .Lgb7_wait
	s_mov_b64 s[8:9], exec
	s_mov_b64 exec, 1
	v_mov_b32_e32 v0, 0x12000
	ds_read_b64 v[2:3], v0
	v_mov_b32_e32 v0, 0x1400
	v_mov_b32_e32 v1, 1
	global_atomic_add v4, v0, v1, s[6:7] sc0
	s_mov_b32 s13, 0
	s_add_u32 s14, s84, 0x2480
	s_addc_u32 s15, s85, 0
	s_waitcnt lgkmcnt(0)
	v_readfirstlane_b32 s10, v2
	v_readfirstlane_b32 s11, v3
	v_mov_b32_e32 v0, 0
	s_nop 3
	s_mul_i32 s10, s10, 7
	s_mul_i32 s11, s11, 6
	s_waitcnt vmcnt(0)
	v_readfirstlane_b32 s12, v4
	s_nop 3
	s_add_u32 s12, s12, 1
	s_cmp_lg_u32 s12, s10
	s_cbranch_scc1 .Lgb7_poll
	buffer_wbl2 sc1
	s_waitcnt vmcnt(0)
	global_atomic_add v0, v1, s[14:15] offset:0
	global_atomic_add v0, v1, s[14:15] offset:256
	global_atomic_add v0, v1, s[14:15] offset:512
	global_atomic_add v0, v1, s[14:15] offset:768
	global_atomic_add v0, v1, s[14:15] offset:1024
	global_atomic_add v0, v1, s[14:15] offset:1280
	global_atomic_add v0, v1, s[14:15] offset:1536
	global_atomic_add v0, v1, s[14:15] offset:1792
	global_atomic_add v0, v1, s[14:15] offset:2048
	global_atomic_add v0, v1, s[14:15] offset:2304
	global_atomic_add v0, v1, s[14:15] offset:2560
	global_atomic_add v0, v1, s[14:15] offset:2816
	global_atomic_add v0, v1, s[14:15] offset:3072
	global_atomic_add v0, v1, s[14:15] offset:3328
	global_atomic_add v0, v1, s[14:15] offset:3584
	global_atomic_add v0, v1, s[14:15] offset:3840

.Lf8_end:
.LBB0_961:
	s_cmp_lt_i32 s61, 9
	s_cbranch_scc1 .LBB0_1015
	s_waitcnt vmcnt(0) lgkmcnt(0)
	s_barrier
	v_readfirstlane_b32 s2, v162
	s_lshl_b32 s3, s33, 8
	s_add_u32 s6, s84, s3
	s_addc_u32 s7, s85, 0
	s_cmp_lg_u32 s2, 0
	s_cbranch_scc1 .Lgb8_wait
	s_mov_b64 s[8:9], exec
	s_mov_b64 exec, 1
	v_mov_b32_e32 v0, 0x12000
	ds_read_b64 v[2:3], v0
	v_mov_b32_e32 v0, 0x1400
	v_mov_b32_e32 v1, 1
	global_atomic_add v4, v0, v1, s[6:7] sc0
	s_mov_b32 s13, 0
	s_add_u32 s14, s84, 0x2480
	s_addc_u32 s15, s85, 0
	s_waitcnt lgkmcnt(0)
	v_readfirstlane_b32 s10, v2
	v_readfirstlane_b32 s11, v3
	v_mov_b32_e32 v0, 0
	s_nop 3
	s_mul_i32 s10, s10, 8
	s_mul_i32 s11, s11, 7
	s_waitcnt vmcnt(0)
	v_readfirstlane_b32 s12, v4
	s_nop 3
	s_add_u32 s12, s12, 1
	s_cmp_lg_u32 s12, s10
	s_cbranch_scc1 .Lgb8_poll
	buffer_wbl2 sc1
	s_waitcnt vmcnt(0)
	global_atomic_add v0, v1, s[14:15] offset:0
	global_atomic_add v0, v1, s[14:15] offset:256
	global_atomic_add v0, v1, s[14:15] offset:512
	global_atomic_add v0, v1, s[14:15] offset:768
	global_atomic_add v0, v1, s[14:15] offset:1024
	global_atomic_add v0, v1, s[14:15] offset:1280
	global_atomic_add v0, v1, s[14:15] offset:1536
	global_atomic_add v0, v1, s[14:15] offset:1792
	global_atomic_add v0, v1, s[14:15] offset:2048
	global_atomic_add v0, v1, s[14:15] offset:2304
	global_atomic_add v0, v1, s[14:15] offset:2560
	global_atomic_add v0, v1, s[14:15] offset:2816
	global_atomic_add v0, v1, s[14:15] offset:3072
	global_atomic_add v0, v1, s[14:15] offset:3328
	global_atomic_add v0, v1, s[14:15] offset:3584
	global_atomic_add v0, v1, s[14:15] offset:3840

.LBB0_1079:
	s_or_b64 exec, exec, s[10:11]
	s_cmp_lt_u32 s61, 11
	s_cbranch_scc1 .LBB0_1133
	s_waitcnt vmcnt(0) lgkmcnt(0)
	s_barrier
	v_readfirstlane_b32 s2, v162
	s_lshl_b32 s3, s33, 8
	s_add_u32 s6, s84, s3
	s_addc_u32 s7, s85, 0
	s_cmp_lg_u32 s2, 0
	s_cbranch_scc1 .Lgb10_wait
	s_mov_b64 s[8:9], exec
	s_mov_b64 exec, 1
	v_mov_b32_e32 v0, 0x12000
	ds_read_b64 v[2:3], v0
	v_mov_b32_e32 v0, 0x1400
	v_mov_b32_e32 v1, 1
	global_atomic_add v4, v0, v1, s[6:7] sc0
	s_mov_b32 s13, 0
	s_add_u32 s14, s84, 0x2480
	s_addc_u32 s15, s85, 0
	s_waitcnt lgkmcnt(0)
	v_readfirstlane_b32 s10, v2
	v_readfirstlane_b32 s11, v3
	v_mov_b32_e32 v0, 0
	s_nop 3
	s_mul_i32 s10, s10, 9
	s_mul_i32 s11, s11, 8
	s_waitcnt vmcnt(0)
	v_readfirstlane_b32 s12, v4
	s_nop 3
	s_add_u32 s12, s12, 1
	s_cmp_lg_u32 s12, s10
	s_cbranch_scc1 .Lgb10_poll
	buffer_wbl2 sc1
	s_waitcnt vmcnt(0)
	global_atomic_add v0, v1, s[14:15] offset:0
	global_atomic_add v0, v1, s[14:15] offset:256
	global_atomic_add v0, v1, s[14:15] offset:512
	global_atomic_add v0, v1, s[14:15] offset:768
	global_atomic_add v0, v1, s[14:15] offset:1024
	global_atomic_add v0, v1, s[14:15] offset:1280
	global_atomic_add v0, v1, s[14:15] offset:1536
	global_atomic_add v0, v1, s[14:15] offset:1792
	global_atomic_add v0, v1, s[14:15] offset:2048
	global_atomic_add v0, v1, s[14:15] offset:2304
	global_atomic_add v0, v1, s[14:15] offset:2560
	global_atomic_add v0, v1, s[14:15] offset:2816
	global_atomic_add v0, v1, s[14:15] offset:3072
	global_atomic_add v0, v1, s[14:15] offset:3328
	global_atomic_add v0, v1, s[14:15] offset:3584
	global_atomic_add v0, v1, s[14:15] offset:3840

.LBB0_1142:
	s_cmp_lt_i32 s61, 12
	s_cbranch_scc1 .LBB0_1196
	s_waitcnt vmcnt(0) lgkmcnt(0)
	s_barrier
	v_readfirstlane_b32 s2, v162
	s_lshl_b32 s3, s33, 8
	s_add_u32 s6, s84, s3
	s_addc_u32 s7, s85, 0
	s_cmp_lg_u32 s2, 0
	s_cbranch_scc1 .Lgb11_wait
	s_mov_b64 s[8:9], exec
	s_mov_b64 exec, 1
	v_mov_b32_e32 v0, 0x12000
	ds_read_b64 v[2:3], v0
	v_mov_b32_e32 v0, 0x1400
	v_mov_b32_e32 v1, 1
	global_atomic_add v4, v0, v1, s[6:7] sc0
	s_mov_b32 s13, 0
	s_add_u32 s14, s84, 0x2480
	s_addc_u32 s15, s85, 0
	s_waitcnt lgkmcnt(0)
	v_readfirstlane_b32 s10, v2
	v_readfirstlane_b32 s11, v3
	v_mov_b32_e32 v0, 0
	s_nop 3
	s_mul_i32 s10, s10, 10
	s_mul_i32 s11, s11, 9
	s_waitcnt vmcnt(0)
	v_readfirstlane_b32 s12, v4
	s_nop 3
	s_add_u32 s12, s12, 1
	s_cmp_lg_u32 s12, s10
	s_cbranch_scc1 .Lgb11_poll
	buffer_wbl2 sc1
	s_waitcnt vmcnt(0)
	global_atomic_add v0, v1, s[14:15] offset:0
	global_atomic_add v0, v1, s[14:15] offset:256
	global_atomic_add v0, v1, s[14:15] offset:512
	global_atomic_add v0, v1, s[14:15] offset:768
	global_atomic_add v0, v1, s[14:15] offset:1024
	global_atomic_add v0, v1, s[14:15] offset:1280
	global_atomic_add v0, v1, s[14:15] offset:1536
	global_atomic_add v0, v1, s[14:15] offset:1792
	global_atomic_add v0, v1, s[14:15] offset:2048
	global_atomic_add v0, v1, s[14:15] offset:2304
	global_atomic_add v0, v1, s[14:15] offset:2560
	global_atomic_add v0, v1, s[14:15] offset:2816
	global_atomic_add v0, v1, s[14:15] offset:3072
	global_atomic_add v0, v1, s[14:15] offset:3328
	global_atomic_add v0, v1, s[14:15] offset:3584
	global_atomic_add v0, v1, s[14:15] offset:3840

.LBB0_1206:
	s_cmp_lt_i32 s61, 13
	s_cbranch_scc1 .LBB0_1260
	s_waitcnt vmcnt(0) lgkmcnt(0)
	s_barrier
	v_readfirstlane_b32 s2, v162
	s_lshl_b32 s3, s33, 8
	s_add_u32 s6, s84, s3
	s_addc_u32 s7, s85, 0
	s_cmp_lg_u32 s2, 0
	s_cbranch_scc1 .Lgb12_wait
	s_mov_b64 s[8:9], exec
	s_mov_b64 exec, 1
	v_mov_b32_e32 v0, 0x12000
	ds_read_b64 v[2:3], v0
	v_mov_b32_e32 v0, 0x1400
	v_mov_b32_e32 v1, 1
	global_atomic_add v4, v0, v1, s[6:7] sc0
	s_mov_b32 s13, 0
	s_add_u32 s14, s84, 0x2480
	s_addc_u32 s15, s85, 0
	s_waitcnt lgkmcnt(0)
	v_readfirstlane_b32 s10, v2
	v_readfirstlane_b32 s11, v3
	v_mov_b32_e32 v0, 0
	s_nop 3
	s_mul_i32 s10, s10, 11
	s_mul_i32 s11, s11, 10
	s_waitcnt vmcnt(0)
	v_readfirstlane_b32 s12, v4
	s_nop 3
	s_add_u32 s12, s12, 1
	s_cmp_lg_u32 s12, s10
	s_cbranch_scc1 .Lgb12_poll
	buffer_wbl2 sc1
	s_waitcnt vmcnt(0)
	global_atomic_add v0, v1, s[14:15] offset:0
	global_atomic_add v0, v1, s[14:15] offset:256
	global_atomic_add v0, v1, s[14:15] offset:512
	global_atomic_add v0, v1, s[14:15] offset:768
	global_atomic_add v0, v1, s[14:15] offset:1024
	global_atomic_add v0, v1, s[14:15] offset:1280
	global_atomic_add v0, v1, s[14:15] offset:1536
	global_atomic_add v0, v1, s[14:15] offset:1792
	global_atomic_add v0, v1, s[14:15] offset:2048
	global_atomic_add v0, v1, s[14:15] offset:2304
	global_atomic_add v0, v1, s[14:15] offset:2560
	global_atomic_add v0, v1, s[14:15] offset:2816
	global_atomic_add v0, v1, s[14:15] offset:3072
	global_atomic_add v0, v1, s[14:15] offset:3328
	global_atomic_add v0, v1, s[14:15] offset:3584
	global_atomic_add v0, v1, s[14:15] offset:3840

.LBB0_1332:
	s_or_b64 exec, exec, s[10:11]
	s_cmp_lt_u32 s61, 15
	s_cbranch_scc1 .LBB0_1386
	s_waitcnt vmcnt(0) lgkmcnt(0)
	s_barrier
	v_readfirstlane_b32 s2, v162
	s_lshl_b32 s3, s33, 8
	s_add_u32 s6, s84, s3
	s_addc_u32 s7, s85, 0
	s_cmp_lg_u32 s2, 0
	s_cbranch_scc1 .Lgb14_wait
	s_mov_b64 s[8:9], exec
	s_mov_b64 exec, 1
	v_mov_b32_e32 v0, 0x12000
	ds_read_b64 v[2:3], v0
	v_mov_b32_e32 v0, 0x1400
	v_mov_b32_e32 v1, 1
	global_atomic_add v4, v0, v1, s[6:7] sc0
	s_mov_b32 s13, 0
	s_add_u32 s14, s84, 0x2480
	s_addc_u32 s15, s85, 0
	s_waitcnt lgkmcnt(0)
	v_readfirstlane_b32 s10, v2
	v_readfirstlane_b32 s11, v3
	v_mov_b32_e32 v0, 0
	s_nop 3
	s_mul_i32 s10, s10, 12
	s_mul_i32 s11, s11, 11
	s_waitcnt vmcnt(0)
	v_readfirstlane_b32 s12, v4
	s_nop 3
	s_add_u32 s12, s12, 1
	s_cmp_lg_u32 s12, s10
	s_cbranch_scc1 .Lgb14_poll
	buffer_wbl2 sc1
	s_waitcnt vmcnt(0)
	global_atomic_add v0, v1, s[14:15] offset:0
	global_atomic_add v0, v1, s[14:15] offset:256
	global_atomic_add v0, v1, s[14:15] offset:512
	global_atomic_add v0, v1, s[14:15] offset:768
	global_atomic_add v0, v1, s[14:15] offset:1024
	global_atomic_add v0, v1, s[14:15] offset:1280
	global_atomic_add v0, v1, s[14:15] offset:1536
	global_atomic_add v0, v1, s[14:15] offset:1792
	global_atomic_add v0, v1, s[14:15] offset:2048
	global_atomic_add v0, v1, s[14:15] offset:2304
	global_atomic_add v0, v1, s[14:15] offset:2560
	global_atomic_add v0, v1, s[14:15] offset:2816
	global_atomic_add v0, v1, s[14:15] offset:3072
	global_atomic_add v0, v1, s[14:15] offset:3328
	global_atomic_add v0, v1, s[14:15] offset:3584
	global_atomic_add v0, v1, s[14:15] offset:3840

.Lf15_end:
.LBB0_1396:
	s_cmp_lt_i32 s61, 16
	s_cbranch_scc1 .LBB0_1450
	s_waitcnt vmcnt(0) lgkmcnt(0)
	s_barrier
	v_readfirstlane_b32 s2, v162
	s_lshl_b32 s3, s33, 8
	s_add_u32 s6, s84, s3
	s_addc_u32 s7, s85, 0
	s_cmp_lg_u32 s2, 0
	s_cbranch_scc1 .Lgb15_wait
	s_mov_b64 s[8:9], exec
	s_mov_b64 exec, 1
	v_mov_b32_e32 v0, 0x12000
	ds_read_b64 v[2:3], v0
	v_mov_b32_e32 v0, 0x1400
	v_mov_b32_e32 v1, 1
	global_atomic_add v4, v0, v1, s[6:7] sc0
	s_mov_b32 s13, 0
	s_add_u32 s14, s84, 0x2480
	s_addc_u32 s15, s85, 0
	s_waitcnt lgkmcnt(0)
	v_readfirstlane_b32 s10, v2
	v_readfirstlane_b32 s11, v3
	v_mov_b32_e32 v0, 0
	s_nop 3
	s_mul_i32 s10, s10, 13
	s_mul_i32 s11, s11, 12
	s_waitcnt vmcnt(0)
	v_readfirstlane_b32 s12, v4
	s_nop 3
	s_add_u32 s12, s12, 1
	s_cmp_lg_u32 s12, s10
	s_cbranch_scc1 .Lgb15_poll
	buffer_wbl2 sc1
	s_waitcnt vmcnt(0)
	global_atomic_add v0, v1, s[14:15] offset:0
	global_atomic_add v0, v1, s[14:15] offset:256
	global_atomic_add v0, v1, s[14:15] offset:512
	global_atomic_add v0, v1, s[14:15] offset:768
	global_atomic_add v0, v1, s[14:15] offset:1024
	global_atomic_add v0, v1, s[14:15] offset:1280
	global_atomic_add v0, v1, s[14:15] offset:1536
	global_atomic_add v0, v1, s[14:15] offset:1792
	global_atomic_add v0, v1, s[14:15] offset:2048
	global_atomic_add v0, v1, s[14:15] offset:2304
	global_atomic_add v0, v1, s[14:15] offset:2560
	global_atomic_add v0, v1, s[14:15] offset:2816
	global_atomic_add v0, v1, s[14:15] offset:3072
	global_atomic_add v0, v1, s[14:15] offset:3328
	global_atomic_add v0, v1, s[14:15] offset:3584
	global_atomic_add v0, v1, s[14:15] offset:3840

.LBB0_1519:
	s_or_b64 exec, exec, s[4:5]
	s_cmp_lt_u32 s61, 18
	s_cbranch_scc1 .LBB0_1573
	s_waitcnt vmcnt(0) lgkmcnt(0)
	s_barrier
	v_readfirstlane_b32 s2, v162
	s_lshl_b32 s3, s33, 8
	s_add_u32 s6, s84, s3
	s_addc_u32 s7, s85, 0
	s_cmp_lg_u32 s2, 0
	s_cbranch_scc1 .Lgb17_wait
	s_mov_b64 s[8:9], exec
	s_mov_b64 exec, 1
	v_mov_b32_e32 v0, 0x12000
	ds_read_b64 v[2:3], v0
	v_mov_b32_e32 v0, 0x1400
	v_mov_b32_e32 v1, 1
	global_atomic_add v4, v0, v1, s[6:7] sc0
	s_mov_b32 s13, 0
	s_add_u32 s14, s84, 0x2480
	s_addc_u32 s15, s85, 0
	s_waitcnt lgkmcnt(0)
	v_readfirstlane_b32 s10, v2
	v_readfirstlane_b32 s11, v3
	v_mov_b32_e32 v0, 0
	s_nop 3
	s_mul_i32 s10, s10, 14
	s_mul_i32 s11, s11, 13
	s_waitcnt vmcnt(0)
	v_readfirstlane_b32 s12, v4
	s_nop 3
	s_add_u32 s12, s12, 1
	s_cmp_lg_u32 s12, s10
	s_cbranch_scc1 .Lgb17_poll
	buffer_wbl2 sc1
	s_waitcnt vmcnt(0)
	global_atomic_add v0, v1, s[14:15] offset:0
	global_atomic_add v0, v1, s[14:15] offset:256
	global_atomic_add v0, v1, s[14:15] offset:512
	global_atomic_add v0, v1, s[14:15] offset:768
	global_atomic_add v0, v1, s[14:15] offset:1024
	global_atomic_add v0, v1, s[14:15] offset:1280
	global_atomic_add v0, v1, s[14:15] offset:1536
	global_atomic_add v0, v1, s[14:15] offset:1792
	global_atomic_add v0, v1, s[14:15] offset:2048
	global_atomic_add v0, v1, s[14:15] offset:2304
	global_atomic_add v0, v1, s[14:15] offset:2560
	global_atomic_add v0, v1, s[14:15] offset:2816
	global_atomic_add v0, v1, s[14:15] offset:3072
	global_atomic_add v0, v1, s[14:15] offset:3328
	global_atomic_add v0, v1, s[14:15] offset:3584
	global_atomic_add v0, v1, s[14:15] offset:3840

.LBB0_1791:
	s_cmp_lt_i32 s61, 19
	s_mov_b64 s[84:85], s[76:77]
	s_cbranch_scc1 .LBB0_1845
	s_waitcnt vmcnt(0) lgkmcnt(0)
	s_barrier
	v_readfirstlane_b32 s2, v162
	s_lshl_b32 s3, s33, 8
	s_add_u32 s6, s84, s3
	s_addc_u32 s7, s85, 0
	s_cmp_lg_u32 s2, 0
	s_cbranch_scc1 .Lgb18_wait
	s_mov_b64 s[8:9], exec
	s_mov_b64 exec, 1
	v_mov_b32_e32 v0, 0x12000
	ds_read_b64 v[2:3], v0
	v_mov_b32_e32 v0, 0x1400
	v_mov_b32_e32 v1, 1
	global_atomic_add v4, v0, v1, s[6:7] sc0
	s_mov_b32 s13, 0
	s_add_u32 s14, s84, 0x2480
	s_addc_u32 s15, s85, 0
	s_waitcnt lgkmcnt(0)
	v_readfirstlane_b32 s10, v2
	v_readfirstlane_b32 s11, v3
	v_mov_b32_e32 v0, 0
	s_nop 3
	s_mul_i32 s10, s10, 15
	s_mul_i32 s11, s11, 14
	s_waitcnt vmcnt(0)
	v_readfirstlane_b32 s12, v4
	s_nop 3
	s_add_u32 s12, s12, 1
	s_cmp_lg_u32 s12, s10
	s_cbranch_scc1 .Lgb18_poll
	buffer_wbl2 sc1
	s_waitcnt vmcnt(0)
	global_atomic_add v0, v1, s[14:15] offset:0
	global_atomic_add v0, v1, s[14:15] offset:256
	global_atomic_add v0, v1, s[14:15] offset:512
	global_atomic_add v0, v1, s[14:15] offset:768
	global_atomic_add v0, v1, s[14:15] offset:1024
	global_atomic_add v0, v1, s[14:15] offset:1280
	global_atomic_add v0, v1, s[14:15] offset:1536
	global_atomic_add v0, v1, s[14:15] offset:1792
	global_atomic_add v0, v1, s[14:15] offset:2048
	global_atomic_add v0, v1, s[14:15] offset:2304
	global_atomic_add v0, v1, s[14:15] offset:2560
	global_atomic_add v0, v1, s[14:15] offset:2816
	global_atomic_add v0, v1, s[14:15] offset:3072
	global_atomic_add v0, v1, s[14:15] offset:3328
	global_atomic_add v0, v1, s[14:15] offset:3584
	global_atomic_add v0, v1, s[14:15] offset:3840

.LBB0_1864:
	s_or_b64 exec, exec, s[4:5]
	s_cmp_lt_i32 s61, 20
	s_cbranch_scc1 .LBB0_1918
	s_waitcnt vmcnt(0) lgkmcnt(0)
	s_barrier
	v_readfirstlane_b32 s2, v162
	s_lshl_b32 s3, s33, 8
	s_add_u32 s6, s84, s3
	s_addc_u32 s7, s85, 0
	s_cmp_lg_u32 s2, 0
	s_cbranch_scc1 .Lgb19_wait
	s_mov_b64 s[8:9], exec
	s_mov_b64 exec, 1
	v_mov_b32_e32 v0, 0x12000
	ds_read_b64 v[2:3], v0
	v_mov_b32_e32 v0, 0x1400
	v_mov_b32_e32 v1, 1
	global_atomic_add v4, v0, v1, s[6:7] sc0
	s_mov_b32 s13, 0
	s_add_u32 s14, s84, 0x2480
	s_addc_u32 s15, s85, 0
	s_waitcnt lgkmcnt(0)
	v_readfirstlane_b32 s10, v2
	v_readfirstlane_b32 s11, v3
	v_mov_b32_e32 v0, 0
	s_nop 3
	s_mul_i32 s10, s10, 16
	s_mul_i32 s11, s11, 15
	s_waitcnt vmcnt(0)
	v_readfirstlane_b32 s12, v4
	s_nop 3
	s_add_u32 s12, s12, 1
	s_cmp_lg_u32 s12, s10
	s_cbranch_scc1 .Lgb19_poll
	buffer_wbl2 sc1
	s_waitcnt vmcnt(0)
	global_atomic_add v0, v1, s[14:15] offset:0
	global_atomic_add v0, v1, s[14:15] offset:256
	global_atomic_add v0, v1, s[14:15] offset:512
	global_atomic_add v0, v1, s[14:15] offset:768
	global_atomic_add v0, v1, s[14:15] offset:1024
	global_atomic_add v0, v1, s[14:15] offset:1280
	global_atomic_add v0, v1, s[14:15] offset:1536
	global_atomic_add v0, v1, s[14:15] offset:1792
	global_atomic_add v0, v1, s[14:15] offset:2048
	global_atomic_add v0, v1, s[14:15] offset:2304
	global_atomic_add v0, v1, s[14:15] offset:2560
	global_atomic_add v0, v1, s[14:15] offset:2816
	global_atomic_add v0, v1, s[14:15] offset:3072
	global_atomic_add v0, v1, s[14:15] offset:3328
	global_atomic_add v0, v1, s[14:15] offset:3584
	global_atomic_add v0, v1, s[14:15] offset:3840

.LBB0_2180:
	s_cmp_lt_i32 s61, 21
	s_cbranch_scc1 .LBB0_2234
	s_waitcnt vmcnt(0) lgkmcnt(0)
	s_barrier
	v_readfirstlane_b32 s2, v162
	s_lshl_b32 s3, s33, 8
	s_add_u32 s6, s84, s3
	s_addc_u32 s7, s85, 0
	s_cmp_lg_u32 s2, 0
	s_cbranch_scc1 .Lgb20_wait
	s_mov_b64 s[8:9], exec
	s_mov_b64 exec, 1
	v_mov_b32_e32 v0, 0x12000
	ds_read_b64 v[2:3], v0
	v_mov_b32_e32 v0, 0x1400
	v_mov_b32_e32 v1, 1
	global_atomic_add v4, v0, v1, s[6:7] sc0
	s_mov_b32 s13, 0
	s_add_u32 s14, s84, 0x2480
	s_addc_u32 s15, s85, 0
	s_waitcnt lgkmcnt(0)
	v_readfirstlane_b32 s10, v2
	v_readfirstlane_b32 s11, v3
	v_mov_b32_e32 v0, 0
	s_nop 3
	s_mul_i32 s10, s10, 17
	s_mul_i32 s11, s11, 16
	s_waitcnt vmcnt(0)
	v_readfirstlane_b32 s12, v4
	s_nop 3
	s_add_u32 s12, s12, 1
	s_cmp_lg_u32 s12, s10
	s_cbranch_scc1 .Lgb20_poll
	buffer_wbl2 sc1
	s_waitcnt vmcnt(0)
	global_atomic_add v0, v1, s[14:15] offset:0
	global_atomic_add v0, v1, s[14:15] offset:256
	global_atomic_add v0, v1, s[14:15] offset:512
	global_atomic_add v0, v1, s[14:15] offset:768
	global_atomic_add v0, v1, s[14:15] offset:1024
	global_atomic_add v0, v1, s[14:15] offset:1280
	global_atomic_add v0, v1, s[14:15] offset:1536
	global_atomic_add v0, v1, s[14:15] offset:1792
	global_atomic_add v0, v1, s[14:15] offset:2048
	global_atomic_add v0, v1, s[14:15] offset:2304
	global_atomic_add v0, v1, s[14:15] offset:2560
	global_atomic_add v0, v1, s[14:15] offset:2816
	global_atomic_add v0, v1, s[14:15] offset:3072
	global_atomic_add v0, v1, s[14:15] offset:3328
	global_atomic_add v0, v1, s[14:15] offset:3584
	global_atomic_add v0, v1, s[14:15] offset:3840

.LBB0_2238:
	s_or_b64 exec, exec, s[6:7]
	s_cmp_lt_u32 s61, 22
	s_cbranch_scc1 .LBB0_2292
	s_waitcnt vmcnt(0) lgkmcnt(0)
	s_barrier
	v_readfirstlane_b32 s2, v162
	s_lshl_b32 s3, s33, 8
	s_add_u32 s6, s84, s3
	s_addc_u32 s7, s85, 0
	s_cmp_lg_u32 s2, 0
	s_cbranch_scc1 .Lgb21_wait
	s_mov_b64 s[8:9], exec
	s_mov_b64 exec, 1
	v_mov_b32_e32 v0, 0x12000
	ds_read_b64 v[2:3], v0
	v_mov_b32_e32 v0, 0x1400
	v_mov_b32_e32 v1, 1
	global_atomic_add v4, v0, v1, s[6:7] sc0
	s_mov_b32 s13, 0
	s_add_u32 s14, s84, 0x2480
	s_addc_u32 s15, s85, 0
	s_waitcnt lgkmcnt(0)
	v_readfirstlane_b32 s10, v2
	v_readfirstlane_b32 s11, v3
	v_mov_b32_e32 v0, 0
	s_nop 3
	s_mul_i32 s10, s10, 18
	s_mul_i32 s11, s11, 17
	s_waitcnt vmcnt(0)
	v_readfirstlane_b32 s12, v4
	s_nop 3
	s_add_u32 s12, s12, 1
	s_cmp_lg_u32 s12, s10
	s_cbranch_scc1 .Lgb21_poll
	buffer_wbl2 sc1
	s_waitcnt vmcnt(0)
	global_atomic_add v0, v1, s[14:15] offset:0
	global_atomic_add v0, v1, s[14:15] offset:256
	global_atomic_add v0, v1, s[14:15] offset:512
	global_atomic_add v0, v1, s[14:15] offset:768
	global_atomic_add v0, v1, s[14:15] offset:1024
	global_atomic_add v0, v1, s[14:15] offset:1280
	global_atomic_add v0, v1, s[14:15] offset:1536
	global_atomic_add v0, v1, s[14:15] offset:1792
	global_atomic_add v0, v1, s[14:15] offset:2048
	global_atomic_add v0, v1, s[14:15] offset:2304
	global_atomic_add v0, v1, s[14:15] offset:2560
	global_atomic_add v0, v1, s[14:15] offset:2816
	global_atomic_add v0, v1, s[14:15] offset:3072
	global_atomic_add v0, v1, s[14:15] offset:3328
	global_atomic_add v0, v1, s[14:15] offset:3584
	global_atomic_add v0, v1, s[14:15] offset:3840

.LBB0_2356:
	s_or_b64 exec, exec, s[10:11]
	s_cmp_lt_u32 s61, 24
	s_cbranch_scc1 .LBB0_2410
	s_waitcnt vmcnt(0) lgkmcnt(0)
	s_barrier
	v_readfirstlane_b32 s2, v162
	s_lshl_b32 s3, s33, 8
	s_add_u32 s6, s84, s3
	s_addc_u32 s7, s85, 0
	s_cmp_lg_u32 s2, 0
	s_cbranch_scc1 .Lgb23_wait
	s_mov_b64 s[8:9], exec
	s_mov_b64 exec, 1
	v_mov_b32_e32 v0, 0x12000
	ds_read_b64 v[2:3], v0
	v_mov_b32_e32 v0, 0x1400
	v_mov_b32_e32 v1, 1
	global_atomic_add v4, v0, v1, s[6:7] sc0
	s_mov_b32 s13, 0
	s_add_u32 s14, s84, 0x2480
	s_addc_u32 s15, s85, 0
	s_waitcnt lgkmcnt(0)
	v_readfirstlane_b32 s10, v2
	v_readfirstlane_b32 s11, v3
	v_mov_b32_e32 v0, 0
	s_nop 3
	s_mul_i32 s10, s10, 19
	s_mul_i32 s11, s11, 18
	s_waitcnt vmcnt(0)
	v_readfirstlane_b32 s12, v4
	s_nop 3
	s_add_u32 s12, s12, 1
	s_cmp_lg_u32 s12, s10
	s_cbranch_scc1 .Lgb23_poll
	buffer_wbl2 sc1
	s_waitcnt vmcnt(0)
	global_atomic_add v0, v1, s[14:15] offset:0
	global_atomic_add v0, v1, s[14:15] offset:256
	global_atomic_add v0, v1, s[14:15] offset:512
	global_atomic_add v0, v1, s[14:15] offset:768
	global_atomic_add v0, v1, s[14:15] offset:1024
	global_atomic_add v0, v1, s[14:15] offset:1280
	global_atomic_add v0, v1, s[14:15] offset:1536
	global_atomic_add v0, v1, s[14:15] offset:1792
	global_atomic_add v0, v1, s[14:15] offset:2048
	global_atomic_add v0, v1, s[14:15] offset:2304
	global_atomic_add v0, v1, s[14:15] offset:2560
	global_atomic_add v0, v1, s[14:15] offset:2816
	global_atomic_add v0, v1, s[14:15] offset:3072
	global_atomic_add v0, v1, s[14:15] offset:3328
	global_atomic_add v0, v1, s[14:15] offset:3584
	global_atomic_add v0, v1, s[14:15] offset:3840

.Lf24_end:
.LBB0_2420:
	s_cmp_lt_i32 s61, 25
	s_cbranch_scc1 .LBB0_2474
	s_waitcnt vmcnt(0) lgkmcnt(0)
	s_barrier
	v_readfirstlane_b32 s2, v162
	s_lshl_b32 s3, s33, 8
	s_add_u32 s6, s84, s3
	s_addc_u32 s7, s85, 0
	s_cmp_lg_u32 s2, 0
	s_cbranch_scc1 .Lgb24_wait
	s_mov_b64 s[8:9], exec
	s_mov_b64 exec, 1
	v_mov_b32_e32 v0, 0x12000
	ds_read_b64 v[2:3], v0
	v_mov_b32_e32 v0, 0x1400
	v_mov_b32_e32 v1, 1
	global_atomic_add v4, v0, v1, s[6:7] sc0
	s_mov_b32 s13, 0
	s_add_u32 s14, s84, 0x2480
	s_addc_u32 s15, s85, 0
	s_waitcnt lgkmcnt(0)
	v_readfirstlane_b32 s10, v2
	v_readfirstlane_b32 s11, v3
	v_mov_b32_e32 v0, 0
	s_nop 3
	s_mul_i32 s10, s10, 20
	s_mul_i32 s11, s11, 19
	s_waitcnt vmcnt(0)
	v_readfirstlane_b32 s12, v4
	s_nop 3
	s_add_u32 s12, s12, 1
	s_cmp_lg_u32 s12, s10
	s_cbranch_scc1 .Lgb24_poll
	buffer_wbl2 sc1
	s_waitcnt vmcnt(0)
	global_atomic_add v0, v1, s[14:15] offset:0
	global_atomic_add v0, v1, s[14:15] offset:256
	global_atomic_add v0, v1, s[14:15] offset:512
	global_atomic_add v0, v1, s[14:15] offset:768
	global_atomic_add v0, v1, s[14:15] offset:1024
	global_atomic_add v0, v1, s[14:15] offset:1280
	global_atomic_add v0, v1, s[14:15] offset:1536
	global_atomic_add v0, v1, s[14:15] offset:1792
	global_atomic_add v0, v1, s[14:15] offset:2048
	global_atomic_add v0, v1, s[14:15] offset:2304
	global_atomic_add v0, v1, s[14:15] offset:2560
	global_atomic_add v0, v1, s[14:15] offset:2816
	global_atomic_add v0, v1, s[14:15] offset:3072
	global_atomic_add v0, v1, s[14:15] offset:3328
	global_atomic_add v0, v1, s[14:15] offset:3584
	global_atomic_add v0, v1, s[14:15] offset:3840

.LBB0_2538:
	s_or_b64 exec, exec, s[10:11]
	s_cmp_lt_u32 s61, 27
	s_cbranch_scc1 .LBB0_2592
	s_waitcnt vmcnt(0) lgkmcnt(0)
	s_barrier
	v_readfirstlane_b32 s2, v162
	s_lshl_b32 s3, s33, 8
	s_add_u32 s6, s84, s3
	s_addc_u32 s7, s85, 0
	s_cmp_lg_u32 s2, 0
	s_cbranch_scc1 .Lgb26_wait
	s_mov_b64 s[8:9], exec
	s_mov_b64 exec, 1
	v_mov_b32_e32 v0, 0x12000
	ds_read_b64 v[2:3], v0
	v_mov_b32_e32 v0, 0x1400
	v_mov_b32_e32 v1, 1
	global_atomic_add v4, v0, v1, s[6:7] sc0
	s_mov_b32 s13, 0
	s_add_u32 s14, s84, 0x2480
	s_addc_u32 s15, s85, 0
	s_waitcnt lgkmcnt(0)
	v_readfirstlane_b32 s10, v2
	v_readfirstlane_b32 s11, v3
	v_mov_b32_e32 v0, 0
	s_nop 3
	s_mul_i32 s10, s10, 21
	s_mul_i32 s11, s11, 20
	s_waitcnt vmcnt(0)
	v_readfirstlane_b32 s12, v4
	s_nop 3
	s_add_u32 s12, s12, 1
	s_cmp_lg_u32 s12, s10
	s_cbranch_scc1 .Lgb26_poll
	buffer_wbl2 sc1
	s_waitcnt vmcnt(0)
	global_atomic_add v0, v1, s[14:15] offset:0
	global_atomic_add v0, v1, s[14:15] offset:256
	global_atomic_add v0, v1, s[14:15] offset:512
	global_atomic_add v0, v1, s[14:15] offset:768
	global_atomic_add v0, v1, s[14:15] offset:1024
	global_atomic_add v0, v1, s[14:15] offset:1280
	global_atomic_add v0, v1, s[14:15] offset:1536
	global_atomic_add v0, v1, s[14:15] offset:1792
	global_atomic_add v0, v1, s[14:15] offset:2048
	global_atomic_add v0, v1, s[14:15] offset:2304
	global_atomic_add v0, v1, s[14:15] offset:2560
	global_atomic_add v0, v1, s[14:15] offset:2816
	global_atomic_add v0, v1, s[14:15] offset:3072
	global_atomic_add v0, v1, s[14:15] offset:3328
	global_atomic_add v0, v1, s[14:15] offset:3584
	global_atomic_add v0, v1, s[14:15] offset:3840

.LBB0_2601:
	s_cmp_lt_i32 s61, 28
	s_cbranch_scc1 .LBB0_2655
	s_waitcnt vmcnt(0) lgkmcnt(0)
	s_barrier
	v_readfirstlane_b32 s2, v162
	s_lshl_b32 s3, s33, 8
	s_add_u32 s6, s84, s3
	s_addc_u32 s7, s85, 0
	s_cmp_lg_u32 s2, 0
	s_cbranch_scc1 .Lgb27_wait
	s_mov_b64 s[8:9], exec
	s_mov_b64 exec, 1
	v_mov_b32_e32 v0, 0x12000
	ds_read_b64 v[2:3], v0
	v_mov_b32_e32 v0, 0x1400
	v_mov_b32_e32 v1, 1
	global_atomic_add v4, v0, v1, s[6:7] sc0
	s_mov_b32 s13, 0
	s_add_u32 s14, s84, 0x2480
	s_addc_u32 s15, s85, 0
	s_waitcnt lgkmcnt(0)
	v_readfirstlane_b32 s10, v2
	v_readfirstlane_b32 s11, v3
	v_mov_b32_e32 v0, 0
	s_nop 3
	s_mul_i32 s10, s10, 22
	s_mul_i32 s11, s11, 21
	s_waitcnt vmcnt(0)
	v_readfirstlane_b32 s12, v4
	s_nop 3
	s_add_u32 s12, s12, 1
	s_cmp_lg_u32 s12, s10
	s_cbranch_scc1 .Lgb27_poll
	buffer_wbl2 sc1
	s_waitcnt vmcnt(0)
	global_atomic_add v0, v1, s[14:15] offset:0
	global_atomic_add v0, v1, s[14:15] offset:256
	global_atomic_add v0, v1, s[14:15] offset:512
	global_atomic_add v0, v1, s[14:15] offset:768
	global_atomic_add v0, v1, s[14:15] offset:1024
	global_atomic_add v0, v1, s[14:15] offset:1280
	global_atomic_add v0, v1, s[14:15] offset:1536
	global_atomic_add v0, v1, s[14:15] offset:1792
	global_atomic_add v0, v1, s[14:15] offset:2048
	global_atomic_add v0, v1, s[14:15] offset:2304
	global_atomic_add v0, v1, s[14:15] offset:2560
	global_atomic_add v0, v1, s[14:15] offset:2816
	global_atomic_add v0, v1, s[14:15] offset:3072
	global_atomic_add v0, v1, s[14:15] offset:3328
	global_atomic_add v0, v1, s[14:15] offset:3584
	global_atomic_add v0, v1, s[14:15] offset:3840

.LBB0_2665:
	s_cmp_lt_i32 s61, 29
	s_cbranch_scc1 .LBB0_2719
	s_waitcnt vmcnt(0) lgkmcnt(0)
	s_barrier
	v_readfirstlane_b32 s2, v162
	s_lshl_b32 s3, s33, 8
	s_add_u32 s6, s84, s3
	s_addc_u32 s7, s85, 0
	s_cmp_lg_u32 s2, 0
	s_cbranch_scc1 .Lgb28_wait
	s_mov_b64 s[8:9], exec
	s_mov_b64 exec, 1
	v_mov_b32_e32 v0, 0x12000
	ds_read_b64 v[2:3], v0
	v_mov_b32_e32 v0, 0x1400
	v_mov_b32_e32 v1, 1
	global_atomic_add v4, v0, v1, s[6:7] sc0
	s_mov_b32 s13, 0
	s_add_u32 s14, s84, 0x2480
	s_addc_u32 s15, s85, 0
	s_waitcnt lgkmcnt(0)
	v_readfirstlane_b32 s10, v2
	v_readfirstlane_b32 s11, v3
	v_mov_b32_e32 v0, 0
	s_nop 3
	s_mul_i32 s10, s10, 23
	s_mul_i32 s11, s11, 22
	s_waitcnt vmcnt(0)
	v_readfirstlane_b32 s12, v4
	s_nop 3
	s_add_u32 s12, s12, 1
	s_cmp_lg_u32 s12, s10
	s_cbranch_scc1 .Lgb28_poll
	buffer_wbl2 sc1
	s_waitcnt vmcnt(0)
	global_atomic_add v0, v1, s[14:15] offset:0
	global_atomic_add v0, v1, s[14:15] offset:256
	global_atomic_add v0, v1, s[14:15] offset:512
	global_atomic_add v0, v1, s[14:15] offset:768
	global_atomic_add v0, v1, s[14:15] offset:1024
	global_atomic_add v0, v1, s[14:15] offset:1280
	global_atomic_add v0, v1, s[14:15] offset:1536
	global_atomic_add v0, v1, s[14:15] offset:1792
	global_atomic_add v0, v1, s[14:15] offset:2048
	global_atomic_add v0, v1, s[14:15] offset:2304
	global_atomic_add v0, v1, s[14:15] offset:2560
	global_atomic_add v0, v1, s[14:15] offset:2816
	global_atomic_add v0, v1, s[14:15] offset:3072
	global_atomic_add v0, v1, s[14:15] offset:3328
	global_atomic_add v0, v1, s[14:15] offset:3584
	global_atomic_add v0, v1, s[14:15] offset:3840

.LBB0_2791:
	s_or_b64 exec, exec, s[10:11]
	s_cmp_lt_u32 s61, 31
	s_cbranch_scc1 .LBB0_2845
	s_waitcnt vmcnt(0) lgkmcnt(0)
	s_barrier
	v_readfirstlane_b32 s2, v162
	s_lshl_b32 s3, s33, 8
	s_add_u32 s6, s84, s3
	s_addc_u32 s7, s85, 0
	s_cmp_lg_u32 s2, 0
	s_cbranch_scc1 .Lgb30_wait
	s_mov_b64 s[8:9], exec
	s_mov_b64 exec, 1
	v_mov_b32_e32 v0, 0x12000
	ds_read_b64 v[2:3], v0
	v_mov_b32_e32 v0, 0x1400
	v_mov_b32_e32 v1, 1
	global_atomic_add v4, v0, v1, s[6:7] sc0
	s_mov_b32 s13, 0
	s_add_u32 s14, s84, 0x2480
	s_addc_u32 s15, s85, 0
	s_waitcnt lgkmcnt(0)
	v_readfirstlane_b32 s10, v2
	v_readfirstlane_b32 s11, v3
	v_mov_b32_e32 v0, 0
	s_nop 3
	s_mul_i32 s10, s10, 24
	s_mul_i32 s11, s11, 23
	s_waitcnt vmcnt(0)
	v_readfirstlane_b32 s12, v4
	s_nop 3
	s_add_u32 s12, s12, 1
	s_cmp_lg_u32 s12, s10
	s_cbranch_scc1 .Lgb30_poll
	buffer_wbl2 sc1
	s_waitcnt vmcnt(0)
	global_atomic_add v0, v1, s[14:15] offset:0
	global_atomic_add v0, v1, s[14:15] offset:256
	global_atomic_add v0, v1, s[14:15] offset:512
	global_atomic_add v0, v1, s[14:15] offset:768
	global_atomic_add v0, v1, s[14:15] offset:1024
	global_atomic_add v0, v1, s[14:15] offset:1280
	global_atomic_add v0, v1, s[14:15] offset:1536
	global_atomic_add v0, v1, s[14:15] offset:1792
	global_atomic_add v0, v1, s[14:15] offset:2048
	global_atomic_add v0, v1, s[14:15] offset:2304
	global_atomic_add v0, v1, s[14:15] offset:2560
	global_atomic_add v0, v1, s[14:15] offset:2816
	global_atomic_add v0, v1, s[14:15] offset:3072
	global_atomic_add v0, v1, s[14:15] offset:3328
	global_atomic_add v0, v1, s[14:15] offset:3584
	global_atomic_add v0, v1, s[14:15] offset:3840

.Lf31_end:
.LBB0_2855:
	s_cmp_lt_i32 s61, 32
	s_cbranch_scc1 .LBB0_2909
	s_waitcnt vmcnt(0) lgkmcnt(0)
	s_barrier
	v_readfirstlane_b32 s2, v162
	s_lshl_b32 s3, s33, 8
	s_add_u32 s6, s84, s3
	s_addc_u32 s7, s85, 0
	s_cmp_lg_u32 s2, 0
	s_cbranch_scc1 .Lgb31_wait
	s_mov_b64 s[8:9], exec
	s_mov_b64 exec, 1
	v_mov_b32_e32 v0, 0x12000
	ds_read_b64 v[2:3], v0
	v_mov_b32_e32 v0, 0x1400
	v_mov_b32_e32 v1, 1
	global_atomic_add v4, v0, v1, s[6:7] sc0
	s_mov_b32 s13, 0
	s_add_u32 s14, s84, 0x2480
	s_addc_u32 s15, s85, 0
	s_waitcnt lgkmcnt(0)
	v_readfirstlane_b32 s10, v2
	v_readfirstlane_b32 s11, v3
	v_mov_b32_e32 v0, 0
	s_nop 3
	s_mul_i32 s10, s10, 25
	s_mul_i32 s11, s11, 24
	s_waitcnt vmcnt(0)
	v_readfirstlane_b32 s12, v4
	s_nop 3
	s_add_u32 s12, s12, 1
	s_cmp_lg_u32 s12, s10
	s_cbranch_scc1 .Lgb31_poll
	buffer_wbl2 sc1
	s_waitcnt vmcnt(0)
	global_atomic_add v0, v1, s[14:15] offset:0
	global_atomic_add v0, v1, s[14:15] offset:256
	global_atomic_add v0, v1, s[14:15] offset:512
	global_atomic_add v0, v1, s[14:15] offset:768
	global_atomic_add v0, v1, s[14:15] offset:1024
	global_atomic_add v0, v1, s[14:15] offset:1280
	global_atomic_add v0, v1, s[14:15] offset:1536
	global_atomic_add v0, v1, s[14:15] offset:1792
	global_atomic_add v0, v1, s[14:15] offset:2048
	global_atomic_add v0, v1, s[14:15] offset:2304
	global_atomic_add v0, v1, s[14:15] offset:2560
	global_atomic_add v0, v1, s[14:15] offset:2816
	global_atomic_add v0, v1, s[14:15] offset:3072
	global_atomic_add v0, v1, s[14:15] offset:3328
	global_atomic_add v0, v1, s[14:15] offset:3584
	global_atomic_add v0, v1, s[14:15] offset:3840
